# strategy 7 on the 1.032x version: NSA selected-loop cross-half max exchange via v_permlane32_swap instead of a ds_bpermute LDS round trip
# speedup vs baseline: 1.0050x; 1.0040x over previous
; DI float shfl_xor_(float v, int mask, int lane) { return __int_as_float(__builtin_amdgcn_ds_bpermute((lane ^ mask) << 2, __float_as_int(v))); }
; DI void flash_update(FlashState& st, f32x16& sc0, f32x16& sc1, const bf16_t* VT, int vs, int qi, int hl) {
;     const bf16x8 va0 = ld_vfrag(VT, qi * vs + 4 * hl), vb0 = ld_vfrag(VT, (32 + qi) * vs + 4 * hl);
;     const bf16x8 va1 = ld_vfrag(VT, qi * vs + 32 + 4 * hl), vb1 = ld_vfrag(VT, (32 + qi) * vs + 32 + 4 * hl);
;     asm volatile("" ::: "memory");
;     float mt = -INFINITY;
; #pragma unroll
;     for (int i = 0; i < 16; ++i) mt = fmaxf(mt, fmaxf(sc0[i], sc1[i]));
;     mt = fmaxf(mt, shfl_xor_(mt, 32, qi + 32 * hl));
;     const float mnew = fmaxf(st.m, mt), muse = (mnew == -INFINITY) ? 0.f : mnew;
;     const float alpha = __builtin_amdgcn_exp2f(st.m - muse);
;     float ls = 0.f;
; #pragma unroll
;     for (int i = 0; i < 16; ++i) { sc0[i] = __builtin_amdgcn_exp2f(sc0[i] - muse); sc1[i] = __builtin_amdgcn_exp2f(sc1[i] - muse); ls += sc0[i] + sc1[i]; }
;     st.l = st.l * alpha + ls; st.m = mnew;
.LBB0_781:
	s_or_b64 exec, exec, s[10:11]
	v_max_f32_e32 v0, v34, v34
	s_nop 4
	v_max_f32_e32 v66, v50, v50
	v_max_f32_e32 v0, v66, v0
	v_max_f32_e32 v66, v35, v35
	v_max_f32_e32 v67, v51, v51
	v_max_f32_e32 v66, v67, v66
	s_mov_b32 s0, 0xff800000
	v_max3_f32 v0, v0, s0, v66
	v_max_f32_e32 v66, v36, v36
	v_max_f32_e32 v67, v52, v52
	v_max_f32_e32 v66, v67, v66
	v_max_f32_e32 v67, v37, v37
	v_max_f32_e32 v68, v53, v53
	v_max_f32_e32 v67, v68, v67
	v_max3_f32 v0, v0, v66, v67
	v_max_f32_e32 v66, v38, v38
	v_max_f32_e32 v67, v54, v54
	v_max_f32_e32 v66, v67, v66
	v_max_f32_e32 v67, v39, v39
	v_max_f32_e32 v68, v55, v55
	v_max_f32_e32 v67, v68, v67
	v_max3_f32 v0, v0, v66, v67
	v_max_f32_e32 v66, v40, v40
	v_max_f32_e32 v67, v56, v56
	v_max_f32_e32 v66, v67, v66
	v_max_f32_e32 v67, v41, v41
	v_max_f32_e32 v68, v57, v57
	v_max_f32_e32 v67, v68, v67
	v_max3_f32 v0, v0, v66, v67
	v_max_f32_e32 v66, v42, v42
	v_max_f32_e32 v67, v58, v58
	v_max_f32_e32 v66, v67, v66
	v_max_f32_e32 v67, v43, v43
	v_max_f32_e32 v68, v59, v59
	v_max_f32_e32 v67, v68, v67
	v_max3_f32 v0, v0, v66, v67
	v_max_f32_e32 v66, v44, v44
	v_max_f32_e32 v67, v60, v60
	v_max_f32_e32 v66, v67, v66
	v_max_f32_e32 v67, v45, v45
	v_max_f32_e32 v68, v61, v61
	v_max_f32_e32 v67, v68, v67
	v_max3_f32 v0, v0, v66, v67
	v_max_f32_e32 v66, v46, v46
	v_max_f32_e32 v67, v62, v62
	v_max_f32_e32 v66, v67, v66
	v_max_f32_e32 v67, v47, v47
	v_max_f32_e32 v68, v63, v63
	v_max_f32_e32 v67, v68, v67
	v_max3_f32 v0, v0, v66, v67
	v_max_f32_e32 v66, v48, v48
	v_max_f32_e32 v67, v64, v64
	v_max_f32_e32 v66, v67, v66
	v_max_f32_e32 v67, v49, v49
	v_max_f32_e32 v68, v65, v65
	v_max_f32_e32 v67, v68, v67
	v_max3_f32 v0, v0, v66, v67
	v_mov_b32_e32 v180, v0
	v_mov_b32_e32 v181, v0
	v_add_u32_e32 v92, 0x2000, v147
	s_nop 0
	v_permlane32_swap_b32_e32 v180, v181
	v_max_f32_e32 v66, v180, v181
	s_waitcnt lgkmcnt(0)
	v_max3_f32 v85, v152, v0, v66
	v_cmp_neq_f32_e32 vcc, s0, v85
	s_nop 1
	v_cndmask_b32_e32 v88, 0, v85, vcc
	v_sub_f32_e32 v0, v50, v88
	v_exp_f32_e32 v89, v0
	v_sub_f32_e32 v0, v34, v88
	v_exp_f32_e32 v90, v0
	v_sub_f32_e32 v0, v51, v88
	v_exp_f32_e32 v74, v0
	v_sub_f32_e32 v0, v35, v88
	v_exp_f32_e32 v0, v0
	v_add_f32_e32 v75, v89, v90
	v_sub_f32_e32 v38, v38, v88
	v_sub_f32_e32 v47, v47, v88
	v_pk_add_f32 v[34:35], v[74:75], v[0:1]
	s_nop 0
	v_pk_add_f32 v[50:51], v[34:35], v[34:35] op_sel_hi:[0,1]
	v_sub_f32_e32 v34, v52, v88
	v_exp_f32_e32 v75, v34
	v_sub_f32_e32 v34, v36, v88
	v_exp_f32_e32 v91, v34
	v_sub_f32_e32 v34, v53, v88
	v_exp_f32_e32 v76, v34
	v_sub_f32_e32 v34, v37, v88
	v_exp_f32_e32 v50, v34
	v_add_f32_e32 v77, v75, v91
	ds_read2_b64 v[34:37], v92 offset0:128 offset1:130
	v_pk_add_f32 v[52:53], v[76:77], v[50:51]
	v_sub_f32_e32 v51, v54, v88
	v_exp_f32_e32 v77, v38
	v_sub_f32_e32 v38, v55, v88
	v_pk_add_f32 v[52:53], v[52:53], v[52:53] op_sel_hi:[0,1]
	v_exp_f32_e32 v51, v51
	v_exp_f32_e32 v78, v38
	v_sub_f32_e32 v38, v39, v88
	v_exp_f32_e32 v52, v38
	v_add_u32_e32 v38, v146, v139
	v_add_f32_e32 v79, v51, v77
	v_add_u32_e32 v93, 0x3000, v38
	v_pk_add_f32 v[38:39], v[78:79], v[52:53]
	s_nop 0
	v_pk_add_f32 v[80:81], v[38:39], v[38:39] op_sel_hi:[0,1]
	v_sub_f32_e32 v38, v56, v88
	v_exp_f32_e32 v53, v38
	v_sub_f32_e32 v38, v40, v88
	v_exp_f32_e32 v79, v38
	v_sub_f32_e32 v38, v57, v88
	v_exp_f32_e32 v82, v38
	v_sub_f32_e32 v38, v41, v88
	v_exp_f32_e32 v80, v38
	v_add_f32_e32 v83, v53, v79
	ds_read2_b64 v[54:57], v93 offset0:192 offset1:194
	ds_read2_b64 v[66:69], v92 offset0:136 offset1:138
	ds_read2_b64 v[70:73], v93 offset0:200 offset1:202
	v_pk_add_f32 v[38:39], v[82:83], v[80:81]
	s_nop 0
	v_pk_add_f32 v[38:39], v[38:39], v[38:39] op_sel_hi:[0,1]
	v_sub_f32_e32 v38, v58, v88
	v_exp_f32_e32 v81, v38
	v_sub_f32_e32 v38, v42, v88
	v_exp_f32_e32 v83, v38
	v_sub_f32_e32 v38, v59, v88
	v_exp_f32_e32 v58, v38
	v_sub_f32_e32 v38, v43, v88
	v_exp_f32_e32 v38, v38
	v_add_f32_e32 v59, v81, v83
	v_sub_f32_e32 v42, v152, v88
	v_exp_f32_e32 v84, v42
	v_pk_add_f32 v[40:41], v[58:59], v[38:39]
	v_sub_f32_e32 v39, v60, v88
	v_pk_add_f32 v[40:41], v[40:41], v[40:41] op_sel_hi:[0,1]
	v_sub_f32_e32 v40, v44, v88
	v_exp_f32_e32 v59, v40
	v_sub_f32_e32 v40, v61, v88
	v_exp_f32_e32 v39, v39
	v_exp_f32_e32 v60, v40
	v_sub_f32_e32 v40, v45, v88
	v_exp_f32_e32 v40, v40
	v_add_f32_e32 v61, v39, v59
	v_pk_mul_f32 v[32:33], v[32:33], v[84:85] op_sel_hi:[1,0]
	v_pk_mul_f32 v[30:31], v[30:31], v[84:85] op_sel_hi:[1,0]
	v_pk_add_f32 v[42:43], v[60:61], v[40:41]
	v_pk_mul_f32 v[28:29], v[28:29], v[84:85] op_sel_hi:[1,0]
	v_pk_add_f32 v[86:87], v[42:43], v[42:43] op_sel_hi:[0,1]
	v_pk_mul_f32 v[26:27], v[26:27], v[84:85] op_sel_hi:[1,0]
	v_pk_mul_f32 v[24:25], v[24:25], v[84:85] op_sel_hi:[1,0]
	v_pk_mul_f32 v[22:23], v[22:23], v[84:85] op_sel_hi:[1,0]
	v_pk_mul_f32 v[20:21], v[20:21], v[84:85] op_sel_hi:[1,0]
	v_pk_mul_f32 v[18:19], v[18:19], v[84:85] op_sel_hi:[1,0]
	v_pk_mul_f32 v[16:17], v[16:17], v[84:85] op_sel_hi:[1,0]
	v_cvt_pk_bf16_f32 v42, v89, v74
	v_cvt_pk_bf16_f32 v43, v75, v76
	v_cvt_pk_bf16_f32 v44, v51, v78
	v_cvt_pk_bf16_f32 v45, v53, v82
	v_pk_mul_f32 v[14:15], v[14:15], v[84:85] op_sel_hi:[1,0]
	v_pk_mul_f32 v[12:13], v[12:13], v[84:85] op_sel_hi:[1,0]
	v_pk_mul_f32 v[10:11], v[10:11], v[84:85] op_sel_hi:[1,0]
	v_pk_mul_f32 v[8:9], v[8:9], v[84:85] op_sel_hi:[1,0]
	v_pk_mul_f32 v[6:7], v[6:7], v[84:85] op_sel_hi:[1,0]
	v_pk_mul_f32 v[4:5], v[4:5], v[84:85] op_sel_hi:[1,0]
	v_pk_mul_f32 v[2:3], v[2:3], v[84:85] op_sel_hi:[1,0]
	s_waitcnt lgkmcnt(3)
; #define MFMA32(a, b, c) __builtin_amdgcn_mfma_f32_32x32x16_bf16((a), (b), (c), 0, 0, 0)
; DI void flash_update(FlashState& st, f32x16& sc0, f32x16& sc1, const bf16_t* VT, int vs, int qi, int hl) {
;     ...
;     for (int i = 0; i < 16; ++i) { sc0[i] = __builtin_amdgcn_exp2f(sc0[i] - muse); sc1[i] = __builtin_amdgcn_exp2f(sc1[i] - muse); ls += sc0[i] + sc1[i]; }
;     st.l = st.l * alpha + ls; st.m = mnew;
;     st.o0 *= alpha; st.o1 *= alpha;
;     {
;         const bf16x8 p0 = pack8(sc0[0], sc0[1], sc0[2], sc0[3], sc0[4], sc0[5], sc0[6], sc0[7]);
;         const bf16x8 p1 = pack8(sc1[0], sc1[1], sc1[2], sc1[3], sc1[4], sc1[5], sc1[6], sc1[7]);
;         const bf16x8 wa0 = ld_vfrag(VT, qi * vs + 16 + 4 * hl), wb0 = ld_vfrag(VT, (32 + qi) * vs + 16 + 4 * hl);
;         const bf16x8 wa1 = ld_vfrag(VT, qi * vs + 48 + 4 * hl), wb1 = ld_vfrag(VT, (32 + qi) * vs + 48 + 4 * hl);
;         st.o0 = MFMA32(va0, p0, st.o0); st.o1 = MFMA32(vb0, p0, st.o1); st.o0 = MFMA32(va1, p1, st.o0); st.o1 = MFMA32(vb1, p1, st.o1);
;         const bf16x8 r0 = pack8(sc0[8], sc0[9], sc0[10], sc0[11], sc0[12], sc0[13], sc0[14], sc0[15]);
;         const bf16x8 r1 = pack8(sc1[8], sc1[9], sc1[10], sc1[11], sc1[12], sc1[13], sc1[14], sc1[15]);
;         st.o0 = MFMA32(wa0, r0, st.o0); st.o1 = MFMA32(wb0, r0, st.o1); st.o0 = MFMA32(wa1, r1, st.o0); st.o1 = MFMA32(wb1, r1, st.o1);
	v_mfma_f32_32x32x16_bf16 v[18:33], v[34:37], v[42:45], v[18:33]
	v_sub_f32_e32 v34, v62, v88
	v_exp_f32_e32 v41, v34
	v_cvt_pk_bf16_f32 v34, v90, v0
	v_cvt_pk_bf16_f32 v35, v91, v50
	v_cvt_pk_bf16_f32 v36, v77, v52
	v_cvt_pk_bf16_f32 v37, v79, v80
	v_exp_f32_e32 v86, v47
	s_waitcnt lgkmcnt(2)
	v_mfma_f32_32x32x16_bf16 v[2:17], v[54:57], v[42:45], v[2:17]
	v_sub_f32_e32 v42, v46, v88
	v_exp_f32_e32 v0, v42
	v_sub_f32_e32 v42, v63, v88
	v_exp_f32_e32 v46, v42
	v_sub_f32_e32 v42, v64, v88
	v_exp_f32_e32 v55, v42
	ds_read2_b64 v[42:45], v92 offset0:132 offset1:134
	s_waitcnt lgkmcnt(2)
	v_mfma_f32_32x32x16_bf16 v[18:33], v[66:69], v[34:37], v[18:33]
	v_cvt_pk_bf16_f32 v50, v81, v58
	v_cvt_pk_bf16_f32 v51, v39, v60
	v_cvt_pk_bf16_f32 v52, v41, v46
	v_add_f32_e32 v47, v41, v0
	v_sub_f32_e32 v39, v48, v88
	v_exp_f32_e32 v48, v39
	v_mov_b32_e32 v152, v85
	s_waitcnt lgkmcnt(1)
	v_mfma_f32_32x32x16_bf16 v[2:17], v[70:73], v[34:37], v[2:17]
	v_sub_f32_e32 v34, v65, v88
	v_exp_f32_e32 v54, v34
	ds_read2_b64 v[34:37], v93 offset0:196 offset1:198
	v_cvt_pk_bf16_f32 v53, v55, v54
	v_add_f32_e32 v55, v55, v48
	s_waitcnt lgkmcnt(1)
	v_mfma_f32_32x32x16_bf16 v[18:33], v[42:45], v[50:53], v[18:33]
	v_add_f32_e64 v42, v46, v86
	v_add_f32_e64 v43, v47, v87
	v_add_f32_e64 v46, v42, v42
	v_add_f32_e64 v47, v42, v43
	ds_read2_b64 v[42:45], v92 offset0:140 offset1:142
	s_waitcnt lgkmcnt(1)
	v_mfma_f32_32x32x16_bf16 v[2:17], v[34:37], v[50:53], v[2:17]
	v_sub_f32_e32 v34, v49, v88
	v_exp_f32_e32 v46, v34
	v_cvt_pk_bf16_f32 v34, v83, v38
	v_cvt_pk_bf16_f32 v35, v59, v40
	ds_read2_b64 v[38:41], v93 offset0:204 offset1:206
	v_cvt_pk_bf16_f32 v36, v0, v86
	v_cvt_pk_bf16_f32 v37, v48, v46
	s_waitcnt lgkmcnt(1)
	s_nop 0
	v_mfma_f32_32x32x16_bf16 v[18:33], v[42:45], v[34:37], v[18:33]
	v_add_f32_e64 v42, v54, v46
	v_add_f32_e64 v43, v55, v47
	v_add_f32_e32 v0, v42, v43
	v_fmac_f32_e32 v0, v140, v84
	v_mov_b32_e32 v140, v0
	s_waitcnt lgkmcnt(0)
	v_mfma_f32_32x32x16_bf16 v[2:17], v[38:41], v[34:37], v[2:17]
